# DMA source-pointer increments moved from the post-barrier segment into the mandatory post-QK nop gap (on top of K/V read hoists)
# baseline (speedup 1.0000x reference)
; __device__ __forceinline__ void qkt(f32x16& p0, f32x16& p1, const char* Ks, const char* Krs, const bf16x8* qr, const char* qro, int r32, int hi, const f32x16& negm) {
;     p0 = negm; p1 = negm;
; #pragma unroll
;     for (int d0 = 0; d0 < 8; ++d0) { const int cb = (d0 * 16 + hi * 8) * 2;
;         const bf16x8 b0 = *reinterpret_cast<const bf16x8*>(Ks + KSWZ(r32, cb));
;         const bf16x8 b1 = *reinterpret_cast<const bf16x8*>(Ks + KSWZ(32 + r32, cb));
;         p0 = __builtin_amdgcn_mfma_f32_32x32x16_bf16(b0, qr[d0], p0, 0, 0, 0);
;         p1 = __builtin_amdgcn_mfma_f32_32x32x16_bf16(b1, qr[d0], p1, 0, 0, 0); }
; #pragma unroll
;     for (int d0 = 0; d0 < 4; ++d0) { const int cb = (d0 * 16 + hi * 8) * 2;
;         const bf16x8 b0 = *reinterpret_cast<const bf16x8*>(Krs + KRSWZ(r32, cb));
;         const bf16x8 b1 = *reinterpret_cast<const bf16x8*>(Krs + KRSWZ(32 + r32, cb));
;         const bf16x8 qf = qr[8 + d0];
;         p0 = __builtin_amdgcn_mfma_f32_32x32x16_bf16(b0, qf, p0, 0, 0, 0);
;         p1 = __builtin_amdgcn_mfma_f32_32x32x16_bf16(b1, qf, p1, 0, 0, 0); }
; }
.LBB0_396:
	s_mov_b32 s6, s70
	s_lshl_b32 s7, s6, 14
	s_add_i32 s10, s7, 0
	v_add3_u32 v68, s10, v227, v211
	ds_read_b128 v[64:67], v68
	s_lshl_b32 s74, vcc_lo, 14
	v_add_u32_e32 v245, s74, v228
	s_lshl_b32 s72, s71, 14
	v_readfirstlane_b32 s100, v245
	s_mov_b32 s101, m0
	s_mov_b32 m0, s100
	s_nop 0
	global_load_lds_dwordx4 v[208:209], off
	s_mov_b32 m0, s101
	s_addk_i32 s100, 0x400
	v_add_u32_e32 v245, s72, v213
	s_mov_b32 s101, m0
	s_mov_b32 m0, s100
	s_nop 0
	global_load_lds_dwordx4 v[206:207], off
	s_mov_b32 m0, s101
	s_lshl_b32 s73, s71, 13
	v_readfirstlane_b32 s100, v245
	s_mov_b32 s101, m0
	s_mov_b32 m0, s100
	s_nop 0
	global_load_lds_dwordx4 v[204:205], off
	s_mov_b32 m0, s101
	s_addk_i32 s100, 0x400
	v_add_u32_e32 v245, s73, v212
	s_mov_b32 s101, m0
	s_mov_b32 m0, s100
	s_nop 0
	global_load_lds_dwordx4 v[202:203], off
	s_mov_b32 m0, s101
	v_readfirstlane_b32 s100, v245
	s_mov_b32 s101, m0
	s_mov_b32 m0, s100
	s_nop 0
	global_load_lds_dwordx4 v[200:201], off
	s_mov_b32 m0, s101
	s_waitcnt lgkmcnt(0)
	v_mfma_f32_32x32x16_bf16 v[112:127], v[64:67], v[128:131], v[80:95]
	ds_read_b128 v[64:67], v68 offset:8192
	v_add3_u32 v68, s10, v226, v211
	s_lshl_b32 s11, s6, 13
	s_mov_b32 s70, vcc_lo
	s_waitcnt lgkmcnt(0)
	v_mfma_f32_32x32x16_bf16 v[96:111], v[64:67], v[128:131], v[80:95]
	ds_read_b128 v[64:67], v68
	s_waitcnt lgkmcnt(0)
	v_mfma_f32_32x32x16_bf16 v[112:127], v[64:67], v[132:135], v[112:127]
	ds_read_b128 v[64:67], v68 offset:8192
	v_add3_u32 v68, s10, v225, v211
	s_waitcnt lgkmcnt(0)
	v_mfma_f32_32x32x16_bf16 v[96:111], v[64:67], v[132:135], v[96:111]
	ds_read_b128 v[64:67], v68
	s_waitcnt lgkmcnt(0)
	v_mfma_f32_32x32x16_bf16 v[112:127], v[64:67], v[136:139], v[112:127]
	ds_read_b128 v[64:67], v68 offset:8192
	v_add3_u32 v68, s10, v224, v211
	s_waitcnt lgkmcnt(0)
	v_mfma_f32_32x32x16_bf16 v[96:111], v[64:67], v[136:139], v[96:111]
	ds_read_b128 v[64:67], v68
	s_waitcnt lgkmcnt(0)
	v_mfma_f32_32x32x16_bf16 v[112:127], v[64:67], v[140:143], v[112:127]
	ds_read_b128 v[64:67], v68 offset:8192
	v_add3_u32 v68, s10, v223, v211
	s_waitcnt lgkmcnt(0)
	v_mfma_f32_32x32x16_bf16 v[96:111], v[64:67], v[140:143], v[96:111]
	ds_read_b128 v[64:67], v68
	s_waitcnt lgkmcnt(0)
	v_mfma_f32_32x32x16_bf16 v[112:127], v[64:67], v[144:147], v[112:127]
	ds_read_b128 v[64:67], v68 offset:8192
	v_add3_u32 v68, s10, v222, v211
	s_waitcnt lgkmcnt(0)
	v_mfma_f32_32x32x16_bf16 v[96:111], v[64:67], v[144:147], v[96:111]
	ds_read_b128 v[64:67], v68
	s_waitcnt lgkmcnt(0)
	v_mfma_f32_32x32x16_bf16 v[112:127], v[64:67], v[148:151], v[112:127]
	ds_read_b128 v[64:67], v68 offset:8192
	v_add3_u32 v68, s10, v221, v211
	s_waitcnt lgkmcnt(0)
	v_mfma_f32_32x32x16_bf16 v[96:111], v[64:67], v[148:151], v[96:111]
	ds_read_b128 v[64:67], v68
	s_waitcnt lgkmcnt(0)
	v_mfma_f32_32x32x16_bf16 v[112:127], v[64:67], v[152:155], v[112:127]
	ds_read_b128 v[64:67], v68 offset:8192
	v_add3_u32 v68, s10, v220, v211
	s_sub_i32 s10, s10, s11
	s_waitcnt lgkmcnt(0)
	v_mfma_f32_32x32x16_bf16 v[96:111], v[64:67], v[152:155], v[96:111]
	ds_read_b128 v[64:67], v68
	s_waitcnt lgkmcnt(0)
	v_mfma_f32_32x32x16_bf16 v[112:127], v[64:67], v[156:159], v[112:127]
	ds_read_b128 v[64:67], v68 offset:8192
	v_add3_u32 v68, s10, v219, v215
	s_waitcnt lgkmcnt(0)
	v_mfma_f32_32x32x16_bf16 v[96:111], v[64:67], v[156:159], v[96:111]
	ds_read_b128 v[64:67], v68 offset:49152
	s_waitcnt lgkmcnt(0)
	v_mfma_f32_32x32x16_bf16 v[112:127], v[64:67], v[164:167], v[112:127]
	ds_read_b128 v[64:67], v68 offset:53248
	v_add3_u32 v68, s10, v218, v215
	s_waitcnt lgkmcnt(0)
	v_mfma_f32_32x32x16_bf16 v[96:111], v[64:67], v[164:167], v[96:111]
	ds_read_b128 v[64:67], v68 offset:49152
	s_waitcnt lgkmcnt(0)
	v_mfma_f32_32x32x16_bf16 v[112:127], v[64:67], v[172:175], v[112:127]
	ds_read_b128 v[64:67], v68 offset:53248
	v_add3_u32 v68, s10, v217, v215
	s_waitcnt lgkmcnt(0)
	v_mfma_f32_32x32x16_bf16 v[96:111], v[64:67], v[172:175], v[96:111]
	ds_read_b128 v[64:67], v68 offset:49152
	s_waitcnt lgkmcnt(0)
	v_mfma_f32_32x32x16_bf16 v[112:127], v[64:67], v[160:163], v[112:127]
	ds_read_b128 v[64:67], v68 offset:53248
	v_add3_u32 v68, s10, v216, v215
	s_waitcnt lgkmcnt(0)
	v_mfma_f32_32x32x16_bf16 v[96:111], v[64:67], v[160:163], v[96:111]
	ds_read_b128 v[64:67], v68 offset:49152
	s_waitcnt lgkmcnt(0)
	v_mfma_f32_32x32x16_bf16 v[112:127], v[64:67], v[168:171], v[112:127]
	ds_read_b128 v[64:67], v68 offset:53248
	s_waitcnt lgkmcnt(0)
	v_mfma_f32_32x32x16_bf16 v[96:111], v[64:67], v[168:171], v[96:111]
	v_lshl_add_u64 v[200:201], v[200:201], 0, s[38:39]
	v_lshl_add_u64 v[202:203], v[202:203], 0, s[36:37]
	v_lshl_add_u64 v[204:205], v[204:205], 0, s[36:37]
	v_lshl_add_u64 v[206:207], v[206:207], 0, s[36:37]
	v_lshl_add_u64 v[208:209], v[208:209], 0, s[36:37]
	s_nop 3
	v_max_f32_e32 v68, v113, v113
	v_max_f32_e32 v69, v112, v112
	v_max_f32_e32 v68, v69, v68
	v_max_f32_e32 v69, v121, v121
	v_max_f32_e32 v70, v120, v120
	v_max_f32_e32 v69, v70, v69
	v_max3_f32 v66, v68, v114, v115
	v_max_f32_e32 v64, v105, v105
	v_max_f32_e32 v65, v104, v104
	v_max_f32_e32 v64, v65, v64
	v_max3_f32 v65, v96, v97, v98
	v_max3_f32 v64, v64, v106, v107
	v_max3_f32 v67, v69, v122, v123
	v_max3_f32 v65, v65, v99, v100
	v_max3_f32 v64, v64, v108, v109
	v_max3_f32 v66, v66, v116, v117
	v_max3_f32 v67, v67, v124, v125
	v_max3_f32 v65, v65, v101, v102
	v_max3_f32 v64, v64, v110, v111
	v_max3_f32 v66, v66, v118, v119
	v_max3_f32 v67, v67, v126, v127
	v_max3_f32 v64, v65, v103, v64
	v_max3_f32 v64, v66, v67, v64
	v_mov_b32_e32 v65, v64
	s_nop 1
	v_permlane32_swap_b32_e32 v64, v65
	v_max_f32_e32 v65, v65, v65
	v_max_f32_e32 v64, v64, v64
	v_max_f32_e32 v64, v64, v65
	v_cmp_ge_f32_e32 vcc, s92, v64
	s_cmp_eq_u64 vcc, exec
	s_cbranch_scc0 .LBB0_404
	v_mov_b32_e32 v229, 1.0

; #define SBAR() __builtin_amdgcn_sched_barrier(0)
; #define WAIT_BAR(N) asm volatile("s_waitcnt vmcnt(" #N ") lgkmcnt(0)\n\ts_barrier" ::: "memory")
; template <int D0> __device__ __forceinline__ void pv_one(f32x16& od, int vb, bf16x8 pa0, bf16x8 pa1, bf16x8 pa2, bf16x8 pa3) {
;     const s16x4 l0 = tr_read<v_rd_off(D0, 0, 0)>(vb), h0 = tr_read<v_rd_off(D0, 0, 1)>(vb), l1 = tr_read<v_rd_off(D0, 1, 0)>(vb), h1 = tr_read<v_rd_off(D0, 1, 1)>(vb);
;     const s16x4 l2 = tr_read<v_rd_off(D0, 2, 0)>(vb), h2 = tr_read<v_rd_off(D0, 2, 1)>(vb), l3 = tr_read<v_rd_off(D0, 3, 0)>(vb), h3 = tr_read<v_rd_off(D0, 3, 1)>(vb);
;     asm volatile("s_waitcnt lgkmcnt(0)" ::: "memory"); SBAR();
;     ...
;     od = __builtin_amdgcn_mfma_f32_32x32x16_bf16(pa0, PK(l0, h0), od, 0, 0, 0);
;     od = __builtin_amdgcn_mfma_f32_32x32x16_bf16(pa1, PK(l1, h1), od, 0, 0, 0);
;     od = __builtin_amdgcn_mfma_f32_32x32x16_bf16(pa2, PK(l2, h2), od, 0, 0, 0);
;     od = __builtin_amdgcn_mfma_f32_32x32x16_bf16(pa3, PK(l3, h3), od, 0, 0, 0);
;     ...
; }
; __device__ __forceinline__ void pv_d0(f32x16* o, int vb, bf16x8 pa0, bf16x8 pa1, bf16x8 pa2, bf16x8 pa3) {
;     pv_one<0>(o[0], vb, pa0, pa1, pa2, pa3); pv_one<1>(o[1], vb, pa0, pa1, pa2, pa3); pv_one<2>(o[2], vb, pa0, pa1, pa2, pa3); pv_one<3>(o[3], vb, pa0, pa1, pa2, pa3);
; __device__ __forceinline__ void attn_unit(const bf16_t* __restrict__ Qb, const bf16_t* __restrict__ Kh, const bf16_t* __restrict__ Vh, const bf16_t* __restrict__ Krh, ...
;     ...
;         if (j + 2 < NT) { WAIT_BAR(3); } else { WAIT_BAR(0); }
;         { const int t_ = s0; s0 = s1; s1 = s2; s2 = t_; }
.LBB0_402:
	v_add_f32_e32 v112, v112, v113
	v_add_u32_e32 v113, s7, v214
	s_waitcnt lgkmcnt(0)
	v_fmac_f32_e32 v112, v198, v229
	v_mfma_f32_32x32x16_bf16 v[0:15], v[96:99], v[64:67], v[0:15]
	ds_read_b64_tr_b16 v[114:115], v113 offset:0x200
	ds_read_b64_tr_b16 v[116:117], v113 offset:0xa00
	v_mfma_f32_32x32x16_bf16 v[0:15], v[104:107], v[68:71], v[0:15]
	ds_read_b64_tr_b16 v[118:119], v113 offset:0x1200
	ds_read_b64_tr_b16 v[120:121], v113 offset:0x1a00
	v_mfma_f32_32x32x16_bf16 v[0:15], v[108:111], v[72:75], v[0:15]
	ds_read_b64_tr_b16 v[122:123], v113 offset:0x2200
	ds_read_b64_tr_b16 v[124:125], v113 offset:0x2a00
	v_mfma_f32_32x32x16_bf16 v[0:15], v[100:103], v[76:79], v[0:15]
	ds_read_b64_tr_b16 v[230:231], v113 offset:0x3200
	ds_read_b64_tr_b16 v[232:233], v113 offset:0x3a00
	s_waitcnt lgkmcnt(0)
	v_mfma_f32_32x32x16_bf16 v[16:31], v[96:99], v[114:117], v[16:31]
	ds_read_b64_tr_b16 v[114:115], v113 offset:0x400
	ds_read_b64_tr_b16 v[116:117], v113 offset:0xc00
	v_mfma_f32_32x32x16_bf16 v[16:31], v[104:107], v[118:121], v[16:31]
	ds_read_b64_tr_b16 v[118:119], v113 offset:0x1400
	ds_read_b64_tr_b16 v[120:121], v113 offset:0x1c00
	v_mfma_f32_32x32x16_bf16 v[16:31], v[108:111], v[122:125], v[16:31]
	ds_read_b64_tr_b16 v[122:123], v113 offset:0x2400
	ds_read_b64_tr_b16 v[124:125], v113 offset:0x2c00
	v_mfma_f32_32x32x16_bf16 v[16:31], v[100:103], v[230:233], v[16:31]
	ds_read_b64_tr_b16 v[230:231], v113 offset:0x3400
	ds_read_b64_tr_b16 v[232:233], v113 offset:0x3c00
	s_waitcnt lgkmcnt(0)
	v_mfma_f32_32x32x16_bf16 v[32:47], v[96:99], v[114:117], v[32:47]
	ds_read_b64_tr_b16 v[114:115], v113 offset:0x600
	ds_read_b64_tr_b16 v[116:117], v113 offset:0xe00
	v_mfma_f32_32x32x16_bf16 v[32:47], v[104:107], v[118:121], v[32:47]
	ds_read_b64_tr_b16 v[118:119], v113 offset:0x1600
	ds_read_b64_tr_b16 v[120:121], v113 offset:0x1e00
	v_mfma_f32_32x32x16_bf16 v[32:47], v[108:111], v[122:125], v[32:47]
	ds_read_b64_tr_b16 v[122:123], v113 offset:0x2600
	ds_read_b64_tr_b16 v[124:125], v113 offset:0x2e00
	v_mfma_f32_32x32x16_bf16 v[32:47], v[100:103], v[230:233], v[32:47]
	ds_read_b64_tr_b16 v[230:231], v113 offset:0x3600
	ds_read_b64_tr_b16 v[232:233], v113 offset:0x3e00
	s_waitcnt lgkmcnt(0)
	v_mfma_f32_32x32x16_bf16 v[48:63], v[96:99], v[114:117], v[48:63]
	s_waitcnt vmcnt(3) lgkmcnt(0)
	s_barrier
	s_add_i32 s28, s28, 1
	v_mfma_f32_32x32x16_bf16 v[48:63], v[104:107], v[118:121], v[48:63]
	s_cmp_eq_u32 s33, s28
	v_mfma_f32_32x32x16_bf16 v[48:63], v[108:111], v[122:125], v[48:63]
	v_mfma_f32_32x32x16_bf16 v[48:63], v[100:103], v[230:233], v[48:63]
	s_cbranch_scc1 .LBB0_405
	s_mov_b32 vcc_lo, s71
	s_mov_b32 s71, s6
	v_mov_b32_e32 v198, v112
	s_branch .LBB0_396
